# mnorm preceded by a bulk pull of its block's Hm / XM / z rows into cache (on top of the mqk variant)
# baseline (speedup 1.0000x reference)
; #define MN_LOAD(tk_) do { const int s_ = (tk_) & (SEQL - 1); hr = *(const u32x2*)(Hm + (size_t)(tk_) * 2048 + c); zr = *(const u32x2*)(Y0 + (size_t)(tk_) * 4096 + 2048 + c); \
;             _Pragma("unroll") for (int j = 0; j < 4; ++j) xr[j] = (s_ - 3 + j >= 0) ? *(const u32x2*)(XM + (size_t)((tk_) - 3 + j) * 2048 + c) : (u32x2){0u, 0u}; } while (0)
; __device__ void mnorm_phase(const Params& p) {
;     ...
;     for (int blk = blockIdx.x; blk < 256; blk += gridDim.x) {
;         u32x2 hr, xr[4], zr;
;     ...
;         MN_LOAD(blk * 64);
.LBB0_594:
	s_lshl_b32 s30, s15, 18
	v_and_b32_e32 v100, 0x3ff, v0
	v_lshlrev_b32_e32 v101, 4, v100
	v_add_u32_e32 v101, s30, v101
	s_add_u32 s32, s64, 0x8000000
	s_addc_u32 s33, s65, 0
	s_lshl_b32 s31, s15, 19
	v_lshrrev_b32_e32 v102, 8, v100
	v_lshlrev_b32_e32 v102, 13, v102
	v_and_b32_e32 v103, 0xff, v100
	v_lshl_add_u32 v102, v103, 4, v102
	v_add_u32_e32 v102, s31, v102
	v_add_u32_e32 v102, 0x1000, v102
	s_add_u32 s34, s64, 0xc000000
	s_addc_u32 s35, s65, 0
	global_load_dwordx4 v[104:107], v101, s[64:65]
	global_load_dwordx4 v[104:107], v101, s[32:33]
	global_load_dwordx4 v[104:107], v102, s[34:35]
	v_add_u32_e32 v101, 0x2000, v101
	v_add_u32_e32 v102, 0x4000, v102
	global_load_dwordx4 v[104:107], v101, s[64:65]
	global_load_dwordx4 v[104:107], v101, s[32:33]
	global_load_dwordx4 v[104:107], v102, s[34:35]
	v_add_u32_e32 v101, 0x2000, v101
	v_add_u32_e32 v102, 0x4000, v102
	global_load_dwordx4 v[104:107], v101, s[64:65]
	global_load_dwordx4 v[104:107], v101, s[32:33]
	global_load_dwordx4 v[104:107], v102, s[34:35]
	v_add_u32_e32 v101, 0x2000, v101
	v_add_u32_e32 v102, 0x4000, v102
	global_load_dwordx4 v[104:107], v101, s[64:65]
	global_load_dwordx4 v[104:107], v101, s[32:33]
	global_load_dwordx4 v[104:107], v102, s[34:35]
	v_add_u32_e32 v101, 0x2000, v101
	v_add_u32_e32 v102, 0x4000, v102
	global_load_dwordx4 v[104:107], v101, s[64:65]
	global_load_dwordx4 v[104:107], v101, s[32:33]
	global_load_dwordx4 v[104:107], v102, s[34:35]
	v_add_u32_e32 v101, 0x2000, v101
	v_add_u32_e32 v102, 0x4000, v102
	global_load_dwordx4 v[104:107], v101, s[64:65]
	global_load_dwordx4 v[104:107], v101, s[32:33]
	global_load_dwordx4 v[104:107], v102, s[34:35]
	v_add_u32_e32 v101, 0x2000, v101
	v_add_u32_e32 v102, 0x4000, v102
	global_load_dwordx4 v[104:107], v101, s[64:65]
	global_load_dwordx4 v[104:107], v101, s[32:33]
	global_load_dwordx4 v[104:107], v102, s[34:35]
	v_add_u32_e32 v101, 0x2000, v101
	v_add_u32_e32 v102, 0x4000, v102
	global_load_dwordx4 v[104:107], v101, s[64:65]
	global_load_dwordx4 v[104:107], v101, s[32:33]
	global_load_dwordx4 v[104:107], v102, s[34:35]
	v_add_u32_e32 v101, 0x2000, v101
	v_add_u32_e32 v102, 0x4000, v102
	global_load_dwordx4 v[104:107], v101, s[64:65]
	global_load_dwordx4 v[104:107], v101, s[32:33]
	global_load_dwordx4 v[104:107], v102, s[34:35]
	v_add_u32_e32 v101, 0x2000, v101
	v_add_u32_e32 v102, 0x4000, v102
	global_load_dwordx4 v[104:107], v101, s[64:65]
	global_load_dwordx4 v[104:107], v101, s[32:33]
	global_load_dwordx4 v[104:107], v102, s[34:35]
	v_add_u32_e32 v101, 0x2000, v101
	v_add_u32_e32 v102, 0x4000, v102
	global_load_dwordx4 v[104:107], v101, s[64:65]
	global_load_dwordx4 v[104:107], v101, s[32:33]
	global_load_dwordx4 v[104:107], v102, s[34:35]
	v_add_u32_e32 v101, 0x2000, v101
	v_add_u32_e32 v102, 0x4000, v102
	global_load_dwordx4 v[104:107], v101, s[64:65]
	global_load_dwordx4 v[104:107], v101, s[32:33]
	global_load_dwordx4 v[104:107], v102, s[34:35]
	v_add_u32_e32 v101, 0x2000, v101
	v_add_u32_e32 v102, 0x4000, v102
	global_load_dwordx4 v[104:107], v101, s[64:65]
	global_load_dwordx4 v[104:107], v101, s[32:33]
	global_load_dwordx4 v[104:107], v102, s[34:35]
	v_add_u32_e32 v101, 0x2000, v101
	v_add_u32_e32 v102, 0x4000, v102
	global_load_dwordx4 v[104:107], v101, s[64:65]
	global_load_dwordx4 v[104:107], v101, s[32:33]
	global_load_dwordx4 v[104:107], v102, s[34:35]
	v_add_u32_e32 v101, 0x2000, v101
	v_add_u32_e32 v102, 0x4000, v102
	global_load_dwordx4 v[104:107], v101, s[64:65]
	global_load_dwordx4 v[104:107], v101, s[32:33]
	global_load_dwordx4 v[104:107], v102, s[34:35]
	v_add_u32_e32 v101, 0x2000, v101
	v_add_u32_e32 v102, 0x4000, v102
	global_load_dwordx4 v[104:107], v101, s[64:65]
	global_load_dwordx4 v[104:107], v101, s[32:33]
	global_load_dwordx4 v[104:107], v102, s[34:35]
	v_add_u32_e32 v101, 0x2000, v101
	v_add_u32_e32 v102, 0x4000, v102
	global_load_dwordx4 v[104:107], v101, s[64:65]
	global_load_dwordx4 v[104:107], v101, s[32:33]
	global_load_dwordx4 v[104:107], v102, s[34:35]
	v_add_u32_e32 v101, 0x2000, v101
	v_add_u32_e32 v102, 0x4000, v102
; #define MN_LOAD(tk_) do { const int s_ = (tk_) & (SEQL - 1); hr = *(const u32x2*)(Hm + (size_t)(tk_) * 2048 + c); zr = *(const u32x2*)(Y0 + (size_t)(tk_) * 4096 + 2048 + c); \
;             _Pragma("unroll") for (int j = 0; j < 4; ++j) xr[j] = (s_ - 3 + j >= 0) ? *(const u32x2*)(XM + (size_t)((tk_) - 3 + j) * 2048 + c) : (u32x2){0u, 0u}; } while (0)
; __device__ void mnorm_phase(const Params& p) {
;     ...
;     for (int blk = blockIdx.x; blk < 256; blk += gridDim.x) {
;         u32x2 hr, xr[4], zr;
;     ...
;         MN_LOAD(blk * 64);
; #pragma unroll 2
;         for (int tt = 0; tt < 64; ++tt) {
;             const int tk = blk * 64 + tt;
;             const u32x2 hc_ = hr, zc_ = zr; const u32x2 xc0 = xr[0], xc1 = xr[1], xc2 = xr[2], xc3 = xr[3];
;             if (tt < 63) MN_LOAD(tk + 1);
	global_load_dwordx4 v[104:107], v101, s[64:65]
	global_load_dwordx4 v[104:107], v101, s[32:33]
	global_load_dwordx4 v[104:107], v102, s[34:35]
	v_add_u32_e32 v101, 0x2000, v101
	v_add_u32_e32 v102, 0x4000, v102
	global_load_dwordx4 v[104:107], v101, s[64:65]
	global_load_dwordx4 v[104:107], v101, s[32:33]
	global_load_dwordx4 v[104:107], v102, s[34:35]
	v_add_u32_e32 v101, 0x2000, v101
	v_add_u32_e32 v102, 0x4000, v102
	global_load_dwordx4 v[104:107], v101, s[64:65]
	global_load_dwordx4 v[104:107], v101, s[32:33]
	global_load_dwordx4 v[104:107], v102, s[34:35]
	v_add_u32_e32 v101, 0x2000, v101
	v_add_u32_e32 v102, 0x4000, v102
	global_load_dwordx4 v[104:107], v101, s[64:65]
	global_load_dwordx4 v[104:107], v101, s[32:33]
	global_load_dwordx4 v[104:107], v102, s[34:35]
	v_add_u32_e32 v101, 0x2000, v101
	v_add_u32_e32 v102, 0x4000, v102
	global_load_dwordx4 v[104:107], v101, s[64:65]
	global_load_dwordx4 v[104:107], v101, s[32:33]
	global_load_dwordx4 v[104:107], v102, s[34:35]
	v_add_u32_e32 v101, 0x2000, v101
	v_add_u32_e32 v102, 0x4000, v102
	global_load_dwordx4 v[104:107], v101, s[64:65]
	global_load_dwordx4 v[104:107], v101, s[32:33]
	global_load_dwordx4 v[104:107], v102, s[34:35]
	v_add_u32_e32 v101, 0x2000, v101
	v_add_u32_e32 v102, 0x4000, v102
	global_load_dwordx4 v[104:107], v101, s[64:65]
	global_load_dwordx4 v[104:107], v101, s[32:33]
	global_load_dwordx4 v[104:107], v102, s[34:35]
	v_add_u32_e32 v101, 0x2000, v101
	v_add_u32_e32 v102, 0x4000, v102
	global_load_dwordx4 v[104:107], v101, s[64:65]
	global_load_dwordx4 v[104:107], v101, s[32:33]
	global_load_dwordx4 v[104:107], v102, s[34:35]
	v_add_u32_e32 v101, 0x2000, v101
	v_add_u32_e32 v102, 0x4000, v102
	global_load_dwordx4 v[104:107], v101, s[64:65]
	global_load_dwordx4 v[104:107], v101, s[32:33]
	global_load_dwordx4 v[104:107], v102, s[34:35]
	v_add_u32_e32 v101, 0x2000, v101
	v_add_u32_e32 v102, 0x4000, v102
	global_load_dwordx4 v[104:107], v101, s[64:65]
	global_load_dwordx4 v[104:107], v101, s[32:33]
	global_load_dwordx4 v[104:107], v102, s[34:35]
	v_add_u32_e32 v101, 0x2000, v101
	v_add_u32_e32 v102, 0x4000, v102
	global_load_dwordx4 v[104:107], v101, s[64:65]
	global_load_dwordx4 v[104:107], v101, s[32:33]
	global_load_dwordx4 v[104:107], v102, s[34:35]
	v_add_u32_e32 v101, 0x2000, v101
	v_add_u32_e32 v102, 0x4000, v102
	global_load_dwordx4 v[104:107], v101, s[64:65]
	global_load_dwordx4 v[104:107], v101, s[32:33]
	global_load_dwordx4 v[104:107], v102, s[34:35]
	v_add_u32_e32 v101, 0x2000, v101
	v_add_u32_e32 v102, 0x4000, v102
	global_load_dwordx4 v[104:107], v101, s[64:65]
	global_load_dwordx4 v[104:107], v101, s[32:33]
	global_load_dwordx4 v[104:107], v102, s[34:35]
	v_add_u32_e32 v101, 0x2000, v101
	v_add_u32_e32 v102, 0x4000, v102
	global_load_dwordx4 v[104:107], v101, s[64:65]
	global_load_dwordx4 v[104:107], v101, s[32:33]
	global_load_dwordx4 v[104:107], v102, s[34:35]
	v_add_u32_e32 v101, 0x2000, v101
	v_add_u32_e32 v102, 0x4000, v102
	global_load_dwordx4 v[104:107], v101, s[64:65]
	global_load_dwordx4 v[104:107], v101, s[32:33]
	global_load_dwordx4 v[104:107], v102, s[34:35]
	v_add_u32_e32 v101, 0x2000, v101
	v_add_u32_e32 v102, 0x4000, v102
	s_lshl_b32 s6, s15, 6
	s_ashr_i32 s7, s6, 31
	s_lshl_b64 s[2:3], s[6:7], 12
	s_lshl_b64 s[8:9], s[6:7], 13
	s_add_u32 s8, s10, s8
	s_addc_u32 s9, s12, s9
	s_waitcnt vmcnt(2)
	v_lshl_add_u64 v[48:49], s[8:9], 0, v[26:27]
	v_lshl_add_u64 v[52:53], v[30:31], 0, s[2:3]
	v_add_co_u32_e32 v54, vcc, 0x1000, v48
	s_and_b32 s16, s15, 63
	s_nop 0
	v_addc_co_u32_e32 v55, vcc, 0, v49, vcc
	global_load_dwordx2 v[50:51], v[52:53], off
	global_load_dwordx2 v[48:49], v[54:55], off
	s_cmp_lg_u32 s16, 0
	s_cselect_b64 s[8:9], -1, 0
	s_cmp_eq_u32 s16, 0
	v_lshl_add_u64 v[52:53], v[32:33], 0, s[2:3]
	s_cbranch_scc1 .LBB0_598
	v_add_co_u32_e32 v54, vcc, 0xffffd000, v52
	s_nop 1
	v_addc_co_u32_e32 v55, vcc, -1, v53, vcc
	global_load_dwordx2 v[56:57], v[54:55], off
	v_cndmask_b32_e64 v2, 0, 1, s[8:9]
	v_cmp_ne_u32_e64 s[2:3], 1, v2
	s_andn2_b64 vcc, exec, s[8:9]
	s_cbranch_vccnz .LBB0_599
